# v41 + one static s_setprio 1 for waves 4-7 during the attention phase (reset at phase exit)
# speedup vs baseline: 1.0022x; 1.0022x over previous
; #define REP(k) for (int rep_ = 0; rep_ < (((DUP_MASK >> (k)) & 1u) ? 2 : 1); ++rep_)
; __global__ void __launch_bounds__(NWAVES * 64, 2) mk_fwd(Args args) {
;     ...
;     if (IN(3)) REP(3) {
;         for (int idx = vcu; idx < 512; idx += G) {
;             const int bh = idx >> 3, qb = idx & 7, b = bh >> 4, h = bh & 15;
;             const size_t row0 = (size_t)b * SEQ + qb * 256, key0 = (size_t)b * SEQ;
;             att::attn_unit(QB + row0 * 3072 + h * 192, KVB + key0 * 4096 + h * 256, KVB + key0 * 4096 + h * 256 + 128, KPE + key0 * 64, AO + row0 * 2048 + h * 128, SEQ, (att::lptr)lds, wave);
.LBB0_446:
	v_readlane_b32 vcc_lo, v237, 2
	s_nop 0
	s_cmp_lt_u32 vcc_lo, 4
	s_cbranch_scc1 .Lattn_prio_skip
	s_setprio 1

; __global__ void __launch_bounds__(NWAVES * 64, 2) mk_fwd(Args args) {
;     ...
;     }
;     if (IN(3) && IN(4)) __syncthreads();
.LBB0_463:
	s_setprio 0
	s_cmp_gt_i32 s87, 4
	s_cselect_b64 s[2:3], -1, 0
	s_and_b64 s[0:1], s[6:7], s[2:3]
	s_andn2_b64 vcc, exec, s[0:1]
	s_cbranch_vccnz .LBB0_465
	s_waitcnt vmcnt(0) lgkmcnt(0)
	s_barrier
